# out phase remap by kind with fewer units for the mLSTM workgroups (7/6/7 + stick-breaking tail on spare workgroups); U GEMM unit-top vmcnt(0) dropped
# baseline (speedup 1.0000x reference)
; template <class Epi, class Sched>
; __device__ __forceinline__ void gemm_phase(PG8_LAS unsigned char* lds, const Gemm g, const Sched& S, const Epi& E) {
;     ...
; #pragma unroll
;         for (int a = 0; a < 2; ++a)
; #pragma unroll
;             for (int b = 0; b < 2; ++b)
; #pragma unroll
;                 for (int m = 0; m < 4; ++m)
; #pragma unroll
;                     for (int n = 0; n < 2; ++n) acc[a][b][m][n] = (f32x4){0.f, 0.f, 0.f, 0.f};
;         cur = nxt; cA = nA; cB = nB; ++ui;
.LBB0_113:
	v_mov_b64_e32 v[0:1], 0x7df
	s_ashr_i32 s9, s8, 31
	v_cmp_lt_i64_e32 vcc, s[12:13], v[0:1]
	s_lshl_b64 s[12:13], s[8:9], 19
	s_add_u32 s12, s26, s12
	s_addc_u32 s13, s27, s13
	s_and_b64 s[14:15], vcc, exec
	s_cselect_b32 s1, s13, s19
	s_cselect_b32 s9, s12, s18
	s_ashr_i32 s7, s6, 31
	s_lshl_b64 s[14:15], s[6:7], 19
	s_add_u32 s14, s28, s14
	s_addc_u32 s15, s29, s15
	s_and_b64 s[22:23], vcc, exec
	s_cselect_b32 s7, s15, s21
	s_cselect_b32 s17, s14, s20
	s_add_u32 s18, s18, 0x40080
	s_addc_u32 s19, s19, 0
	s_add_u32 s40, s20, 0x100
	v_mov_b32_e32 v0, 0
	s_addc_u32 s41, s21, 0
	s_mov_b32 s59, -2
	v_mov_b32_e32 v1, v0
	v_mov_b32_e32 v2, v0
	v_mov_b32_e32 v3, v0
	v_mov_b32_e32 v4, v0
	v_mov_b32_e32 v5, v0
	v_mov_b32_e32 v6, v0
	v_mov_b32_e32 v7, v0
	v_mov_b32_e32 v12, v0
	v_mov_b32_e32 v13, v0
	v_mov_b32_e32 v14, v0
	v_mov_b32_e32 v15, v0
	v_mov_b32_e32 v20, v0
	v_mov_b32_e32 v21, v0
	v_mov_b32_e32 v22, v0
	v_mov_b32_e32 v23, v0
	v_mov_b32_e32 v28, v0
	v_mov_b32_e32 v29, v0
	v_mov_b32_e32 v30, v0
	v_mov_b32_e32 v31, v0
	v_mov_b32_e32 v36, v0
	v_mov_b32_e32 v37, v0
	v_mov_b32_e32 v38, v0
	v_mov_b32_e32 v39, v0
	v_mov_b32_e32 v44, v0
	v_mov_b32_e32 v45, v0
	v_mov_b32_e32 v46, v0
	v_mov_b32_e32 v47, v0
	v_mov_b32_e32 v52, v0
	v_mov_b32_e32 v53, v0
	v_mov_b32_e32 v54, v0
	v_mov_b32_e32 v55, v0
	v_mov_b32_e32 v8, v0
	v_mov_b32_e32 v9, v0
	v_mov_b32_e32 v10, v0
	v_mov_b32_e32 v11, v0
	v_mov_b32_e32 v16, v0
	v_mov_b32_e32 v17, v0
	v_mov_b32_e32 v18, v0
	v_mov_b32_e32 v19, v0
	v_mov_b32_e32 v24, v0
	v_mov_b32_e32 v25, v0
	v_mov_b32_e32 v26, v0
	v_mov_b32_e32 v27, v0
	v_mov_b32_e32 v32, v0
	v_mov_b32_e32 v33, v0
	v_mov_b32_e32 v34, v0
	v_mov_b32_e32 v35, v0
	v_mov_b32_e32 v40, v0
	v_mov_b32_e32 v41, v0
	v_mov_b32_e32 v42, v0
	v_mov_b32_e32 v43, v0
	v_mov_b32_e32 v48, v0
	v_mov_b32_e32 v49, v0
	v_mov_b32_e32 v50, v0
	v_mov_b32_e32 v51, v0
	v_mov_b32_e32 v56, v0
	v_mov_b32_e32 v57, v0
	v_mov_b32_e32 v58, v0
	v_mov_b32_e32 v59, v0
	v_mov_b32_e32 v60, v0
	v_mov_b32_e32 v61, v0
	v_mov_b32_e32 v62, v0
	v_mov_b32_e32 v63, v0
	s_nop 0
	v_mov_b32_e32 v64, v0
	v_mov_b32_e32 v65, v0
	v_mov_b32_e32 v66, v0
	v_mov_b32_e32 v67, v0
	v_mov_b32_e32 v68, v0
	v_mov_b32_e32 v69, v0
	v_mov_b32_e32 v70, v0
	v_mov_b32_e32 v71, v0
	v_mov_b32_e32 v76, v0
	v_mov_b32_e32 v77, v0
	v_mov_b32_e32 v78, v0
	v_mov_b32_e32 v79, v0
	v_mov_b32_e32 v84, v0
	v_mov_b32_e32 v85, v0
	v_mov_b32_e32 v86, v0
	v_mov_b32_e32 v87, v0
	v_mov_b32_e32 v92, v0
	v_mov_b32_e32 v93, v0
	v_mov_b32_e32 v94, v0
	v_mov_b32_e32 v95, v0
	v_mov_b32_e32 v100, v0
	v_mov_b32_e32 v101, v0
	v_mov_b32_e32 v102, v0
	v_mov_b32_e32 v103, v0
	v_mov_b32_e32 v108, v0
	v_mov_b32_e32 v109, v0
	v_mov_b32_e32 v110, v0
	v_mov_b32_e32 v111, v0
	v_mov_b32_e32 v116, v0
	v_mov_b32_e32 v117, v0
	v_mov_b32_e32 v118, v0
	v_mov_b32_e32 v119, v0
	v_mov_b32_e32 v72, v0
	v_mov_b32_e32 v73, v0
	v_mov_b32_e32 v74, v0
	v_mov_b32_e32 v75, v0
	v_mov_b32_e32 v80, v0
	v_mov_b32_e32 v81, v0
	v_mov_b32_e32 v82, v0
	v_mov_b32_e32 v83, v0
	v_mov_b32_e32 v88, v0
	v_mov_b32_e32 v89, v0
	v_mov_b32_e32 v90, v0
	v_mov_b32_e32 v91, v0
	v_mov_b32_e32 v96, v0
	v_mov_b32_e32 v97, v0
	v_mov_b32_e32 v98, v0
	v_mov_b32_e32 v99, v0
	v_mov_b32_e32 v104, v0
	v_mov_b32_e32 v105, v0
	v_mov_b32_e32 v106, v0
	v_mov_b32_e32 v107, v0
	v_mov_b32_e32 v112, v0
	v_mov_b32_e32 v113, v0
	v_mov_b32_e32 v114, v0
	v_mov_b32_e32 v115, v0
	v_mov_b32_e32 v120, v0
	v_mov_b32_e32 v121, v0
	v_mov_b32_e32 v122, v0
	v_mov_b32_e32 v123, v0
	v_mov_b32_e32 v124, v0
	v_mov_b32_e32 v125, v0
	v_mov_b32_e32 v126, v0
	v_mov_b32_e32 v127, v0

; __global__ void __launch_bounds__(NT) mega(P p) {
;     ...
;     for (int u = blockIdx.x; u < 3 * NUNIT + (NUNIT - SB_M1); u += gridDim.x) {
;       if (u >= 3 * NUNIT) { sb_unit(p, SB_M1 + (u - 3 * NUNIT), smem); continue; }
;       const int kind = u / NUNIT, uu = u % NUNIT;
;       if (kind == 0) out_unit<0>(p, layer, uu, smem);
;       else if (kind == 1) out_unit<1>(p, layer, uu, smem);
;       else out_unit<2>(p, layer, uu, smem);
;     }
.LBB0_481:
	s_or_b64 exec, exec, s[0:1]
	v_readlane_b32 s0, v254, 44
	v_readlane_b32 s1, v254, 45
	s_andn2_b64 vcc, exec, s[0:1]
	s_waitcnt lgkmcnt(0)
	s_barrier
	s_cbranch_vccnz .LBB0_673
	v_readlane_b32 s0, v254, 61
	s_lshl_b32 s96, s0, 8
	v_readlane_b32 s12, v254, 25
	s_lshl_b64 s[0:1], s[96:97], 2
	v_readlane_b32 s24, v254, 37
	v_readlane_b32 s25, v254, 38
	s_add_u32 s60, s24, s0
	v_readlane_b32 s22, v254, 35
	s_addc_u32 s62, s25, s1
	v_readlane_b32 s23, v254, 36
	s_add_u32 s63, s22, s0
	v_readlane_b32 s14, v254, 27
	s_addc_u32 s64, s23, s1
	v_readlane_b32 s15, v254, 28
	s_add_u32 s65, s14, s0
	s_addc_u32 s66, s15, s1
	s_nop 0
	s_mul_i32 s33, s53, 7
	s_movk_i32 s67, 7
	s_movk_i32 s69, 0x208
	s_cmpk_lt_u32 s53, 75
	s_cbranch_scc1 .Lom_done
	s_sub_i32 s33, s53, 75
	s_mul_i32 s33, s33, 6
	s_addk_i32 s33, 0x208
	s_movk_i32 s67, 6
	s_movk_i32 s69, 0x410
	s_cmpk_lt_u32 s53, 162
	s_cbranch_scc1 .Lom_done
	s_sub_i32 s33, s53, 162
	s_mul_i32 s33, s33, 7
	s_addk_i32 s33, 0x410
	s_movk_i32 s67, 7
	s_movk_i32 s69, 0x618
	s_cmpk_lt_u32 s53, 237
	s_cbranch_scc1 .Lom_done
	s_sub_i32 s33, s53, 237
	s_lshl_b32 s33, s33, 1
	s_addk_i32 s33, 0x618
	s_min_u32 s33, s33, 0x637
	s_movk_i32 s67, 2
	s_movk_i32 s69, 0x638
.Lom_done:
	s_add_i32 s68, s33, 0xfffffbd0
	s_mov_b32 s58, 0
	v_readlane_b32 s13, v254, 26
	v_readlane_b32 s16, v254, 29
	v_readlane_b32 s17, v254, 30
	v_readlane_b32 s18, v254, 31
	v_readlane_b32 s19, v254, 32
	v_readlane_b32 s20, v254, 33
	v_readlane_b32 s21, v254, 34
	v_readlane_b32 s26, v254, 39
	v_readlane_b32 s27, v254, 40
	s_branch .LBB0_485

; __global__ void __launch_bounds__(NT) mega(P p) {
;     ...
;     for (int u = blockIdx.x; u < 3 * NUNIT + (NUNIT - SB_M1); u += gridDim.x) {
;       if (u >= 3 * NUNIT) { sb_unit(p, SB_M1 + (u - 3 * NUNIT), smem); continue; }
;       const int kind = u / NUNIT, uu = u % NUNIT;
;       if (kind == 0) out_unit<0>(p, layer, uu, smem);
;       else if (kind == 1) out_unit<1>(p, layer, uu, smem);
;       else out_unit<2>(p, layer, uu, smem);
;     }
.LBB0_484:
	s_add_i32 s33, s33, 1
	s_add_i32 s58, s58, 1
	s_add_i32 s68, s33, 0xfffffbd0
	s_cmp_ge_u32 s33, s69
	s_cselect_b32 s57, s67, s58
	s_cmp_ge_u32 s57, s67
	v_mov_b32_e32 v208, v30
	global_store_dwordx2 v[4:5], v[0:1], off offset:96
	s_cbranch_scc1 .LBB0_672
